# MLP-down epilogue: 6 of the 8 second-half residual loads hoisted next to the first-half loads (all in flight together)
# baseline (speedup 1.0000x reference)
; __device__ __forceinline__ unsigned cvt_pk_bf16(float lo, float hi) { unsigned r; asm volatile("v_cvt_pk_bf16_f32 %0, %1, %2" : "=v"(r) : "v"(lo), "v"(hi)); return r; }
;     __device__ __forceinline__ void operator()(const f32x4 (&acc)[2][2][4][2], const Unit& u, int wr, int wc, int fr, int fq, int, PG8_LAS unsigned char*) const {
;     ...
;         for (int ai = 0; ai < 2; ++ai) {
;             u32x4 xw[4][2];
; #pragma unroll
;             for (int m = 0; m < 4; ++m)
; #pragma unroll
;                 for (int bj = 0; bj < 2; ++bj) xw[m][bj] = *(const u32x4*)(xb + (size_t)(row0 + ai * HALF + m * 16) * 1024 + col0 + bj * HALF);
; #pragma unroll
;             for (int m = 0; m < 4; ++m) {
;                 const int row = row0 + ai * HALF + m * 16; const size_t off = (size_t)row * 1024 + col0;
;                 float s = 0.f;
; #pragma unroll
;                 for (int bj = 0; bj < 2; ++bj) {
;                     const u32x4 xv = xw[m][bj];
;                     const f32x4 xo0 = {__builtin_bit_cast(float, xv.x << 16), __builtin_bit_cast(float, xv.x & 0xffff0000u), __builtin_bit_cast(float, xv.y << 16), __builtin_bit_cast(float, xv.y & 0xffff0000u)};
;                     const f32x4 xo1 = {__builtin_bit_cast(float, xv.z << 16), __builtin_bit_cast(float, xv.z & 0xffff0000u), __builtin_bit_cast(float, xv.w << 16), __builtin_bit_cast(float, xv.w & 0xffff0000u)};
;                     const f32x4 o0 = xo0 + acc[ai][bj][m][0] * csv[bj][0], o1 = xo1 + acc[ai][bj][m][1] * csv[bj][1];
;                     u32x4 w; w.x = cvt_pk_bf16(o0[0], o0[1]); w.y = cvt_pk_bf16(o0[2], o0[3]); w.z = cvt_pk_bf16(o1[0], o1[1]); w.w = cvt_pk_bf16(o1[2], o1[3]);
;                     if (!dry) *(u32x4*)(xb + off + bj * HALF) = w;
; #pragma unroll
;                     for (int q = 0; q < 4; ++q) { const unsigned ww = w[q]; const float ra = __builtin_bit_cast(float, ww << 16), rb = __builtin_bit_cast(float, ww & 0xffff0000u); s += ra * ra + rb * rb; }
;                 }
;                 s += __shfl_xor(s, 16); s += __shfl_xor(s, 32);
;                 if (fq == 0 && !dry) ssq_next[(size_t)row * 16 + u.pn * 4 + wc] = s;
.LBB0_1848:
	v_lshl_or_b32 v162, s16, 8, v190
	v_ashrrev_i32_e32 v163, 31, v162
	v_lshl_add_u32 v166, s68, 8, v188
	v_lshlrev_b64 v[128:129], 1, v[162:163]
	v_ashrrev_i32_e32 v167, 31, v166
	v_lshl_add_u64 v[164:165], s[10:11], 0, v[128:129]
	v_lshlrev_b64 v[130:131], 11, v[166:167]
	v_lshl_add_u64 v[132:133], v[164:165], 0, v[130:131]
	global_load_dwordx4 v[176:179], v[132:133], off
	global_load_dwordx4 v[192:195], v[132:133], off offset:256
	v_or_b32_e32 v184, 16, v166
	v_or_b32_e32 v180, 32, v166
	v_or_b32_e32 v168, 48, v166
	v_ashrrev_i32_e32 v185, 31, v184
	v_ashrrev_i32_e32 v181, 31, v180
	v_ashrrev_i32_e32 v169, 31, v168
	v_lshlrev_b64 v[186:187], 11, v[184:185]
	v_lshlrev_b64 v[182:183], 11, v[180:181]
	v_lshlrev_b64 v[170:171], 11, v[168:169]
	v_lshl_add_u64 v[130:131], s[10:11], 0, v[130:131]
	v_lshl_add_u64 v[132:133], v[164:165], 0, v[186:187]
	v_lshl_add_u64 v[134:135], v[164:165], 0, v[182:183]
	v_lshl_add_u64 v[172:173], v[164:165], 0, v[170:171]
	v_lshl_add_u64 v[196:197], v[130:131], 0, v[128:129]
	global_load_dwordx4 v[148:151], v[132:133], off
	global_load_dwordx4 v[144:147], v[132:133], off offset:256
	global_load_dwordx4 v[140:143], v[134:135], off
	global_load_dwordx4 v[136:139], v[134:135], off offset:256
	s_nop 0
	global_load_dwordx4 v[132:135], v[172:173], off
	global_load_dwordx4 v[128:131], v[172:173], off offset:256
	v_add_u32_e32 v204, 0x80, v166
	v_ashrrev_i32_e32 v205, 31, v204
	v_lshlrev_b64 v[204:205], 11, v[204:205]
	v_lshl_add_u64 v[204:205], v[164:165], 0, v[204:205]
	global_load_dwordx4 v[228:231], v[204:205], off
	global_load_dwordx4 v[232:235], v[204:205], off offset:256
	v_add_u32_e32 v206, 0x90, v166
	v_ashrrev_i32_e32 v207, 31, v206
	v_lshlrev_b64 v[206:207], 11, v[206:207]
	v_lshl_add_u64 v[206:207], v[164:165], 0, v[206:207]
	global_load_dwordx4 v[236:239], v[206:207], off
	global_load_dwordx4 v[240:243], v[206:207], off offset:256
	v_add_u32_e32 v226, 0xa0, v166
	v_ashrrev_i32_e32 v227, 31, v226
	v_lshlrev_b64 v[226:227], 11, v[226:227]
	v_lshl_add_u64 v[226:227], v[164:165], 0, v[226:227]
	global_load_dwordx4 v[244:247], v[226:227], off
	global_load_dwordx4 v[248:251], v[226:227], off offset:256
	s_lshl_b32 s0, s16, 2
	s_ashr_i32 s1, s0, 31
	s_waitcnt vmcnt(6)
	v_lshlrev_b32_e32 v172, 16, v176
	v_and_b32_e32 v173, 0xffff0000, v176
	v_lshlrev_b32_e32 v176, 16, v177
	v_and_b32_e32 v177, 0xffff0000, v177
	v_lshlrev_b32_e32 v198, 16, v178
	v_and_b32_e32 v199, 0xffff0000, v178
	v_lshlrev_b32_e32 v202, 16, v194
	v_and_b32_e32 v203, 0xffff0000, v194
	v_lshlrev_b32_e32 v178, 16, v179
	v_and_b32_e32 v179, 0xffff0000, v179
	v_lshlrev_b32_e32 v194, 16, v195
	v_and_b32_e32 v195, 0xffff0000, v195
	v_pk_add_f32 v[126:127], v[126:127], v[176:177]
	v_pk_add_f32 v[124:125], v[124:125], v[172:173]
	v_pk_add_f32 v[120:121], v[120:121], v[198:199]
	v_pk_add_f32 v[176:177], v[112:113], v[202:203]
	v_cvt_pk_bf16_f32 v112, v124, v125
	v_cvt_pk_bf16_f32 v113, v126, v127
	v_pk_add_f32 v[122:123], v[122:123], v[178:179]
	v_pk_add_f32 v[172:173], v[114:115], v[194:195]
	v_cvt_pk_bf16_f32 v114, v120, v121
	v_cvt_pk_bf16_f32 v115, v122, v123
	global_store_dwordx4 v[196:197], v[112:115], off
	v_lshlrev_b32_e32 v120, 16, v112
	v_lshlrev_b32_e32 v121, 16, v113
	v_and_b32_e32 v112, 0xffff0000, v112
	v_and_b32_e32 v113, 0xffff0000, v113
	v_lshlrev_b32_e32 v200, 16, v192
	v_and_b32_e32 v201, 0xffff0000, v192
	v_lshlrev_b32_e32 v122, 16, v114
	v_and_b32_e32 v114, 0xffff0000, v114
	v_mul_f32_e32 v112, v112, v112
	v_mul_f32_e32 v113, v113, v113
	v_pk_add_f32 v[116:117], v[116:117], v[200:201]
	v_lshlrev_b32_e32 v123, 16, v115
	v_and_b32_e32 v115, 0xffff0000, v115
	v_mul_f32_e32 v114, v114, v114
	v_fmac_f32_e32 v112, v120, v120
	v_fmac_f32_e32 v113, v121, v121
	v_lshlrev_b32_e32 v192, 16, v193
	v_and_b32_e32 v193, 0xffff0000, v193
	v_cvt_pk_bf16_f32 v116, v116, v117
	v_mul_f32_e32 v115, v115, v115
	v_and_b32_e32 v125, 0xffff0000, v116
	v_fmac_f32_e32 v114, v122, v122
	v_add_f32_e32 v112, v112, v113
	v_pk_add_f32 v[118:119], v[118:119], v[192:193]
	v_lshlrev_b32_e32 v124, 16, v116
	v_cvt_pk_bf16_f32 v117, v118, v119
	v_fmac_f32_e32 v115, v123, v123
	v_and_b32_e32 v127, 0xffff0000, v117
	v_mul_f32_e32 v120, v125, v125
	v_add_f32_e32 v112, v112, v114
	v_cvt_pk_bf16_f32 v118, v176, v177
	v_cvt_pk_bf16_f32 v119, v172, v173
	v_lshlrev_b32_e32 v126, 16, v117
	v_and_b32_e32 v173, 0xffff0000, v118
	v_mul_f32_e32 v121, v127, v127
	v_fmac_f32_e32 v120, v124, v124
	v_add_f32_e32 v112, v112, v115
	v_lshlrev_b32_e32 v172, 16, v118
	v_mul_f32_e32 v122, v173, v173
	v_fmac_f32_e32 v121, v126, v126
	v_add_f32_e32 v112, v112, v120
	v_and_b32_e32 v114, 0xffff0000, v119
	v_fmac_f32_e32 v122, v172, v172
	v_add_f32_e32 v112, v112, v121
	v_lshlrev_b32_e32 v113, 16, v119
	v_mul_f32_e32 v114, v114, v114
	v_add_f32_e32 v112, v112, v122
	v_fmac_f32_e32 v114, v113, v113
	v_add_f32_e32 v113, v112, v114
	v_and_b32_e32 v114, 64, v213
	v_xor_b32_e32 v112, 16, v213
	v_add_u32_e32 v115, 64, v114
	v_cmp_lt_i32_e32 vcc, v112, v115
	global_store_dwordx4 v[196:197], v[116:119], off offset:256
	s_nop 0
	v_cndmask_b32_e32 v112, v213, v112, vcc
	v_lshlrev_b32_e32 v112, 2, v112
	ds_bpermute_b32 v114, v112, v113
	s_waitcnt lgkmcnt(0)
	v_add_f32_e32 v114, v113, v114
	v_xor_b32_e32 v113, 32, v213
	v_cmp_lt_i32_e32 vcc, v113, v115
	s_nop 1
	v_cndmask_b32_e32 v113, v213, v113, vcc
	v_lshlrev_b32_e32 v113, 2, v113
	ds_bpermute_b32 v115, v113, v114
	s_and_saveexec_b64 s[54:55], s[40:41]
	s_cbranch_execz .LBB0_1850
	v_lshlrev_b64 v[116:117], 6, v[166:167]
	v_lshl_add_u64 v[116:117], s[24:25], 0, v[116:117]
	v_lshl_add_u64 v[116:117], s[0:1], 2, v[116:117]
	s_lshl_b32 s16, s63, 2
	v_lshl_add_u64 v[116:117], v[116:117], 0, s[16:17]
	s_waitcnt lgkmcnt(0)
	v_add_f32_e32 v114, v114, v115
	global_store_dword v[116:117], v114, off

; __device__ __forceinline__ unsigned cvt_pk_bf16(float lo, float hi) { unsigned r; asm volatile("v_cvt_pk_bf16_f32 %0, %1, %2" : "=v"(r) : "v"(lo), "v"(hi)); return r; }
;     __device__ __forceinline__ void operator()(const f32x4 (&acc)[2][2][4][2], const Unit& u, int wr, int wc, int fr, int fq, int, PG8_LAS unsigned char*) const {
;     ...
;                 for (int bj = 0; bj < 2; ++bj) xw[m][bj] = *(const u32x4*)(xb + (size_t)(row0 + ai * HALF + m * 16) * 1024 + col0 + bj * HALF);
; #pragma unroll
;             for (int m = 0; m < 4; ++m) {
;                 const int row = row0 + ai * HALF + m * 16; const size_t off = (size_t)row * 1024 + col0;
;                 float s = 0.f;
; #pragma unroll
;                 for (int bj = 0; bj < 2; ++bj) {
;                     const u32x4 xv = xw[m][bj];
;                     const f32x4 xo0 = {__builtin_bit_cast(float, xv.x << 16), __builtin_bit_cast(float, xv.x & 0xffff0000u), __builtin_bit_cast(float, xv.y << 16), __builtin_bit_cast(float, xv.y & 0xffff0000u)};
;                     const f32x4 xo1 = {__builtin_bit_cast(float, xv.z << 16), __builtin_bit_cast(float, xv.z & 0xffff0000u), __builtin_bit_cast(float, xv.w << 16), __builtin_bit_cast(float, xv.w & 0xffff0000u)};
;                     const f32x4 o0 = xo0 + acc[ai][bj][m][0] * csv[bj][0], o1 = xo1 + acc[ai][bj][m][1] * csv[bj][1];
;                     u32x4 w; w.x = cvt_pk_bf16(o0[0], o0[1]); w.y = cvt_pk_bf16(o0[2], o0[3]); w.z = cvt_pk_bf16(o1[0], o1[1]); w.w = cvt_pk_bf16(o1[2], o1[3]);
;                     if (!dry) *(u32x4*)(xb + off + bj * HALF) = w;
; #pragma unroll
;                     for (int q = 0; q < 4; ++q) { const unsigned ww = w[q]; const float ra = __builtin_bit_cast(float, ww << 16), rb = __builtin_bit_cast(float, ww & 0xffff0000u); s += ra * ra + rb * rb; }
;                 }
;                 s += __shfl_xor(s, 16); s += __shfl_xor(s, 32);
;                 if (fq == 0 && !dry) ssq_next[(size_t)row * 16 + u.pn * 4 + wc] = s;
.LBB0_1856:
	s_or_b64 exec, exec, s[54:55]
	v_add_u32_e32 v104, 0x80, v166
	v_ashrrev_i32_e32 v105, 31, v104
	v_lshlrev_b64 v[110:111], 11, v[104:105]
	s_waitcnt lgkmcnt(0)
	v_lshl_add_u64 v[64:65], v[164:165], 0, v[110:111]
	v_add_u32_e32 v100, 0x90, v166
	v_ashrrev_i32_e32 v101, 31, v100
	v_add_u32_e32 v96, 0xa0, v166
	v_lshlrev_b64 v[102:103], 11, v[100:101]
	v_ashrrev_i32_e32 v97, 31, v96
	v_add_u32_e32 v92, 0xb0, v166
	v_lshl_add_u64 v[64:65], v[164:165], 0, v[102:103]
	v_lshlrev_b64 v[98:99], 11, v[96:97]
	v_ashrrev_i32_e32 v93, 31, v92
	v_lshl_add_u64 v[64:65], v[164:165], 0, v[98:99]
	v_lshlrev_b64 v[94:95], 11, v[92:93]
	v_lshl_add_u64 v[64:65], v[164:165], 0, v[94:95]
	global_load_dwordx4 v[68:71], v[64:65], off
	s_nop 0
	global_load_dwordx4 v[64:67], v[64:65], off offset:256
	s_waitcnt vmcnt(10)
	v_lshlrev_b32_e32 v114, 16, v228
	v_and_b32_e32 v115, 0xffff0000, v228
	v_lshlrev_b32_e32 v106, 16, v229
	v_and_b32_e32 v107, 0xffff0000, v229
	v_lshlrev_b32_e32 v116, 16, v230
	v_and_b32_e32 v117, 0xffff0000, v230
	v_lshlrev_b32_e32 v108, 16, v231
	v_and_b32_e32 v109, 0xffff0000, v231
	v_pk_add_f32 v[60:61], v[60:61], v[114:115]
	v_pk_add_f32 v[62:63], v[62:63], v[106:107]
	v_pk_add_f32 v[106:107], v[58:59], v[108:109]
	v_pk_add_f32 v[58:59], v[56:57], v[116:117]
	v_cvt_pk_bf16_f32 v56, v60, v61
	v_lshl_add_u64 v[60:61], s[10:11], 0, v[110:111]
	v_lshl_add_u64 v[60:61], v[162:163], 1, v[60:61]
	v_cvt_pk_bf16_f32 v57, v62, v63
	v_cvt_pk_bf16_f32 v58, v58, v59
	v_cvt_pk_bf16_f32 v59, v106, v107
	global_store_dwordx4 v[60:61], v[56:59], off
	v_lshlrev_b32_e32 v62, 16, v56
	s_waitcnt vmcnt(7)
	v_and_b32_e32 v63, 0xffff0000, v234
	v_and_b32_e32 v56, 0xffff0000, v56
	v_mul_f32_e32 v56, v56, v56
	v_fmac_f32_e32 v56, v62, v62
	v_lshlrev_b32_e32 v62, 16, v57
	v_and_b32_e32 v57, 0xffff0000, v57
	v_mul_f32_e32 v57, v57, v57
	v_fmac_f32_e32 v57, v62, v62
	v_add_f32_e32 v56, v56, v57
	v_lshlrev_b32_e32 v57, 16, v58
	v_and_b32_e32 v58, 0xffff0000, v58
	v_mul_f32_e32 v58, v58, v58
	v_fmac_f32_e32 v58, v57, v57
	v_add_f32_e32 v56, v56, v58
	v_and_b32_e32 v58, 0xffff0000, v59
	v_lshlrev_b32_e32 v57, 16, v59
	v_mul_f32_e32 v58, v58, v58
	v_fmac_f32_e32 v58, v57, v57
	v_add_f32_e32 v106, v56, v58
	v_lshlrev_b32_e32 v56, 16, v232
	v_and_b32_e32 v57, 0xffff0000, v232
	v_lshlrev_b32_e32 v58, 16, v233
	v_and_b32_e32 v59, 0xffff0000, v233
	v_lshlrev_b32_e32 v62, 16, v234
	v_lshlrev_b32_e32 v88, 16, v235
	v_and_b32_e32 v89, 0xffff0000, v235
	v_pk_add_f32 v[52:53], v[52:53], v[56:57]
	v_pk_add_f32 v[56:57], v[50:51], v[88:89]
	v_pk_add_f32 v[50:51], v[48:49], v[62:63]
	v_cvt_pk_bf16_f32 v48, v52, v53
	v_pk_add_f32 v[54:55], v[54:55], v[58:59]
	v_lshlrev_b32_e32 v52, 16, v48
	v_cvt_pk_bf16_f32 v49, v54, v55
	v_cvt_pk_bf16_f32 v50, v50, v51
	v_cvt_pk_bf16_f32 v51, v56, v57
	global_store_dwordx4 v[60:61], v[48:51], off offset:256
	s_nop 1
	v_and_b32_e32 v48, 0xffff0000, v48
	v_mul_f32_e32 v48, v48, v48
	v_fmac_f32_e32 v48, v52, v52
	v_lshlrev_b32_e32 v52, 16, v49
	v_and_b32_e32 v49, 0xffff0000, v49
	v_mul_f32_e32 v49, v49, v49
	v_add_f32_e32 v48, v106, v48
	v_fmac_f32_e32 v49, v52, v52
	v_add_f32_e32 v48, v48, v49
	v_lshlrev_b32_e32 v49, 16, v50
	v_and_b32_e32 v50, 0xffff0000, v50
	v_mul_f32_e32 v50, v50, v50
	v_fmac_f32_e32 v50, v49, v49
	v_add_f32_e32 v48, v48, v50
	v_and_b32_e32 v50, 0xffff0000, v51
	v_lshlrev_b32_e32 v49, 16, v51
	v_mul_f32_e32 v50, v50, v50
	v_fmac_f32_e32 v50, v49, v49
	v_add_f32_e32 v48, v48, v50
	ds_bpermute_b32 v49, v112, v48
	s_waitcnt lgkmcnt(0)
	v_add_f32_e32 v48, v48, v49
	ds_bpermute_b32 v49, v113, v48
	s_and_saveexec_b64 s[54:55], s[40:41]
	s_cbranch_execz .LBB0_1858
	v_lshlrev_b64 v[50:51], 6, v[104:105]
	v_lshl_add_u64 v[50:51], s[24:25], 0, v[50:51]
	v_lshl_add_u64 v[50:51], s[0:1], 2, v[50:51]
	s_lshl_b32 s16, s63, 2
	v_lshl_add_u64 v[50:51], v[50:51], 0, s[16:17]
	s_waitcnt lgkmcnt(0)
	v_add_f32_e32 v48, v48, v49
	global_store_dword v[50:51], v48, off
; __device__ __forceinline__ unsigned cvt_pk_bf16(float lo, float hi) { unsigned r; asm volatile("v_cvt_pk_bf16_f32 %0, %1, %2" : "=v"(r) : "v"(lo), "v"(hi)); return r; }
;     __device__ __forceinline__ void operator()(const f32x4 (&acc)[2][2][4][2], const Unit& u, int wr, int wc, int fr, int fq, int, PG8_LAS unsigned char*) const {
;     ...
;                 for (int bj = 0; bj < 2; ++bj) xw[m][bj] = *(const u32x4*)(xb + (size_t)(row0 + ai * HALF + m * 16) * 1024 + col0 + bj * HALF);
; #pragma unroll
;             for (int m = 0; m < 4; ++m) {
;                 const int row = row0 + ai * HALF + m * 16; const size_t off = (size_t)row * 1024 + col0;
;                 float s = 0.f;
; #pragma unroll
;                 for (int bj = 0; bj < 2; ++bj) {
;                     const u32x4 xv = xw[m][bj];
;                     const f32x4 xo0 = {__builtin_bit_cast(float, xv.x << 16), __builtin_bit_cast(float, xv.x & 0xffff0000u), __builtin_bit_cast(float, xv.y << 16), __builtin_bit_cast(float, xv.y & 0xffff0000u)};
;                     const f32x4 xo1 = {__builtin_bit_cast(float, xv.z << 16), __builtin_bit_cast(float, xv.z & 0xffff0000u), __builtin_bit_cast(float, xv.w << 16), __builtin_bit_cast(float, xv.w & 0xffff0000u)};
;                     const f32x4 o0 = xo0 + acc[ai][bj][m][0] * csv[bj][0], o1 = xo1 + acc[ai][bj][m][1] * csv[bj][1];
;                     u32x4 w; w.x = cvt_pk_bf16(o0[0], o0[1]); w.y = cvt_pk_bf16(o0[2], o0[3]); w.z = cvt_pk_bf16(o1[0], o1[1]); w.w = cvt_pk_bf16(o1[2], o1[3]);
;                     if (!dry) *(u32x4*)(xb + off + bj * HALF) = w;
; #pragma unroll
;                     for (int q = 0; q < 4; ++q) { const unsigned ww = w[q]; const float ra = __builtin_bit_cast(float, ww << 16), rb = __builtin_bit_cast(float, ww & 0xffff0000u); s += ra * ra + rb * rb; }
;                 }
;                 s += __shfl_xor(s, 16); s += __shfl_xor(s, 32);
;                 if (fq == 0 && !dry) ssq_next[(size_t)row * 16 + u.pn * 4 + wc] = s;
.LBB0_1858:
	s_or_b64 exec, exec, s[54:55]
	s_waitcnt vmcnt(7)
	v_lshlrev_b32_e32 v48, 16, v236
	s_waitcnt lgkmcnt(0)
	v_and_b32_e32 v49, 0xffff0000, v236
	v_lshlrev_b32_e32 v52, 16, v238
	v_and_b32_e32 v53, 0xffff0000, v238
	v_lshlrev_b32_e32 v54, 16, v239
	v_and_b32_e32 v55, 0xffff0000, v239
	v_pk_add_f32 v[44:45], v[44:45], v[48:49]
	v_lshlrev_b32_e32 v50, 16, v237
	v_and_b32_e32 v51, 0xffff0000, v237
	v_pk_add_f32 v[48:49], v[42:43], v[54:55]
	v_pk_add_f32 v[42:43], v[40:41], v[52:53]
	v_cvt_pk_bf16_f32 v40, v44, v45
	v_lshl_add_u64 v[44:45], s[10:11], 0, v[102:103]
	v_pk_add_f32 v[46:47], v[46:47], v[50:51]
	v_lshl_add_u64 v[44:45], v[162:163], 1, v[44:45]
	v_cvt_pk_bf16_f32 v41, v46, v47
	v_cvt_pk_bf16_f32 v42, v42, v43
	v_cvt_pk_bf16_f32 v43, v48, v49
	global_store_dwordx4 v[44:45], v[40:43], off
	v_lshlrev_b32_e32 v46, 16, v40
	s_waitcnt vmcnt(7)
	v_and_b32_e32 v47, 0xffff0000, v242
	v_and_b32_e32 v40, 0xffff0000, v40
	v_mul_f32_e32 v40, v40, v40
	v_fmac_f32_e32 v40, v46, v46
	v_lshlrev_b32_e32 v46, 16, v41
	v_and_b32_e32 v41, 0xffff0000, v41
	v_mul_f32_e32 v41, v41, v41
	v_fmac_f32_e32 v41, v46, v46
	v_add_f32_e32 v40, v40, v41
	v_lshlrev_b32_e32 v41, 16, v42
	v_and_b32_e32 v42, 0xffff0000, v42
	v_mul_f32_e32 v42, v42, v42
	v_fmac_f32_e32 v42, v41, v41
	v_add_f32_e32 v40, v40, v42
	v_and_b32_e32 v42, 0xffff0000, v43
	v_lshlrev_b32_e32 v41, 16, v43
	v_mul_f32_e32 v42, v42, v42
	v_fmac_f32_e32 v42, v41, v41
	v_add_f32_e32 v50, v40, v42
	v_lshlrev_b32_e32 v40, 16, v240
	v_and_b32_e32 v41, 0xffff0000, v240
	v_lshlrev_b32_e32 v46, 16, v242
	v_lshlrev_b32_e32 v42, 16, v241
	v_and_b32_e32 v43, 0xffff0000, v241
	v_lshlrev_b32_e32 v48, 16, v243
	v_and_b32_e32 v49, 0xffff0000, v243
	v_pk_add_f32 v[36:37], v[36:37], v[40:41]
	v_pk_add_f32 v[32:33], v[32:33], v[46:47]
	v_pk_add_f32 v[38:39], v[38:39], v[42:43]
	v_pk_add_f32 v[40:41], v[34:35], v[48:49]
	v_cvt_pk_bf16_f32 v34, v36, v37
	v_cvt_pk_bf16_f32 v35, v38, v39
	v_cvt_pk_bf16_f32 v36, v32, v33
	s_nop 0
	v_and_b32_e32 v33, 0xffff0000, v34
	v_lshlrev_b32_e32 v32, 16, v34
	v_mul_f32_e32 v33, v33, v33
	v_fmac_f32_e32 v33, v32, v32
	v_and_b32_e32 v38, 0xffff0000, v35
	v_add_f32_e32 v32, v50, v33
	v_lshlrev_b32_e32 v33, 16, v35
	v_mul_f32_e32 v38, v38, v38
	v_fmac_f32_e32 v38, v33, v33
	v_add_f32_e32 v32, v32, v38
	v_and_b32_e32 v38, 0xffff0000, v36
	v_lshlrev_b32_e32 v33, 16, v36
	v_mul_f32_e32 v38, v38, v38
	v_fmac_f32_e32 v38, v33, v33
	v_cvt_pk_bf16_f32 v37, v40, v41
	v_add_f32_e32 v32, v32, v38
	v_and_b32_e32 v38, 0xffff0000, v37
	v_lshlrev_b32_e32 v33, 16, v37
	v_mul_f32_e32 v38, v38, v38
	v_fmac_f32_e32 v38, v33, v33
	v_add_f32_e32 v32, v32, v38
	ds_bpermute_b32 v33, v112, v32
	global_store_dwordx4 v[44:45], v[34:37], off offset:256
	s_waitcnt lgkmcnt(0)
	v_add_f32_e32 v32, v32, v33
	ds_bpermute_b32 v33, v113, v32
	s_and_saveexec_b64 s[54:55], s[40:41]
	s_cbranch_execz .LBB0_1860
	v_lshlrev_b64 v[34:35], 6, v[100:101]
	v_lshl_add_u64 v[34:35], s[24:25], 0, v[34:35]
	v_lshl_add_u64 v[34:35], s[0:1], 2, v[34:35]
	s_lshl_b32 s16, s63, 2
	v_lshl_add_u64 v[34:35], v[34:35], 0, s[16:17]
	s_waitcnt lgkmcnt(0)
	v_add_f32_e32 v32, v32, v33
	global_store_dword v[34:35], v32, off
.LBB0_1860:
	s_or_b64 exec, exec, s[54:55]
	s_waitcnt vmcnt(7)
	v_lshlrev_b32_e32 v32, 16, v244
	s_waitcnt lgkmcnt(0)
	v_and_b32_e32 v33, 0xffff0000, v244
	v_lshlrev_b32_e32 v36, 16, v246
	v_and_b32_e32 v37, 0xffff0000, v246
	v_lshlrev_b32_e32 v38, 16, v247
	v_and_b32_e32 v39, 0xffff0000, v247
	v_pk_add_f32 v[28:29], v[28:29], v[32:33]
	v_lshlrev_b32_e32 v34, 16, v245
	v_and_b32_e32 v35, 0xffff0000, v245
	v_pk_add_f32 v[32:33], v[26:27], v[38:39]
	v_pk_add_f32 v[26:27], v[24:25], v[36:37]
	v_cvt_pk_bf16_f32 v24, v28, v29
	v_lshl_add_u64 v[28:29], s[10:11], 0, v[98:99]
	v_pk_add_f32 v[30:31], v[30:31], v[34:35]
	v_lshl_add_u64 v[28:29], v[162:163], 1, v[28:29]
	v_cvt_pk_bf16_f32 v25, v30, v31
	v_cvt_pk_bf16_f32 v26, v26, v27
	v_cvt_pk_bf16_f32 v27, v32, v33
	global_store_dwordx4 v[28:29], v[24:27], off
	v_lshlrev_b32_e32 v30, 16, v24
	s_waitcnt vmcnt(7)
	v_and_b32_e32 v31, 0xffff0000, v250
	v_and_b32_e32 v24, 0xffff0000, v24
	v_mul_f32_e32 v24, v24, v24
	v_fmac_f32_e32 v24, v30, v30
	v_lshlrev_b32_e32 v30, 16, v25
	v_and_b32_e32 v25, 0xffff0000, v25
	v_mul_f32_e32 v25, v25, v25
	v_fmac_f32_e32 v25, v30, v30
	v_add_f32_e32 v24, v24, v25
	v_lshlrev_b32_e32 v25, 16, v26
	v_and_b32_e32 v26, 0xffff0000, v26
	v_mul_f32_e32 v26, v26, v26
	v_fmac_f32_e32 v26, v25, v25
	v_add_f32_e32 v24, v24, v26
	v_and_b32_e32 v26, 0xffff0000, v27
	v_lshlrev_b32_e32 v25, 16, v27
	v_mul_f32_e32 v26, v26, v26
	v_fmac_f32_e32 v26, v25, v25
	v_add_f32_e32 v34, v24, v26
	v_lshlrev_b32_e32 v24, 16, v248
	v_and_b32_e32 v25, 0xffff0000, v248
	v_lshlrev_b32_e32 v30, 16, v250
	v_lshlrev_b32_e32 v26, 16, v249
	v_and_b32_e32 v27, 0xffff0000, v249
	v_lshlrev_b32_e32 v32, 16, v251
	v_and_b32_e32 v33, 0xffff0000, v251
	v_pk_add_f32 v[20:21], v[20:21], v[24:25]
	v_pk_add_f32 v[16:17], v[16:17], v[30:31]
	v_pk_add_f32 v[22:23], v[22:23], v[26:27]
	v_pk_add_f32 v[24:25], v[18:19], v[32:33]
	v_cvt_pk_bf16_f32 v18, v20, v21
	v_cvt_pk_bf16_f32 v19, v22, v23
	v_cvt_pk_bf16_f32 v20, v16, v17
	s_nop 0
	v_and_b32_e32 v17, 0xffff0000, v18
	v_lshlrev_b32_e32 v16, 16, v18
	v_mul_f32_e32 v17, v17, v17
	v_fmac_f32_e32 v17, v16, v16
	v_and_b32_e32 v22, 0xffff0000, v19
	v_add_f32_e32 v16, v34, v17
	v_lshlrev_b32_e32 v17, 16, v19
	v_mul_f32_e32 v22, v22, v22
	v_fmac_f32_e32 v22, v17, v17
	v_add_f32_e32 v16, v16, v22
	v_and_b32_e32 v22, 0xffff0000, v20
	v_lshlrev_b32_e32 v17, 16, v20
	v_mul_f32_e32 v22, v22, v22
	v_fmac_f32_e32 v22, v17, v17
	v_cvt_pk_bf16_f32 v21, v24, v25
	v_add_f32_e32 v16, v16, v22
	v_and_b32_e32 v22, 0xffff0000, v21
	v_lshlrev_b32_e32 v17, 16, v21
	v_mul_f32_e32 v22, v22, v22
	v_fmac_f32_e32 v22, v17, v17
	v_add_f32_e32 v16, v16, v22
	ds_bpermute_b32 v17, v112, v16
	global_store_dwordx4 v[28:29], v[18:21], off offset:256
	s_waitcnt lgkmcnt(0)
	v_add_f32_e32 v16, v16, v17
	ds_bpermute_b32 v17, v113, v16
	s_and_saveexec_b64 s[54:55], s[40:41]
	s_cbranch_execz .LBB0_1862
	v_lshlrev_b64 v[18:19], 6, v[96:97]
	v_lshl_add_u64 v[18:19], s[24:25], 0, v[18:19]
	v_lshl_add_u64 v[18:19], s[0:1], 2, v[18:19]
	s_lshl_b32 s16, s63, 2
	v_lshl_add_u64 v[18:19], v[18:19], 0, s[16:17]
	s_waitcnt lgkmcnt(0)
	v_add_f32_e32 v16, v16, v17
	global_store_dword v[18:19], v16, off
